# prep bf16(x) loop: the four intra-row stages of the wave sum use DPP row rotations instead of LDS bpermute round trips
# baseline (speedup 1.0000x reference)
.LBB0_30:
	global_load_dword v75, v[66:67], off
	global_load_dword v76, v[68:69], off
	global_load_dword v77, v[70:71], off
	global_load_dword v78, v[72:73], off
	v_and_b32_e32 v79, 0x7e, v0
	s_add_i32 s14, 0, 0x10200
	v_lshl_or_b32 v80, v0, 2, 4
	v_lshl_add_u32 v79, v79, 2, s14
	v_add_u32_e32 v80, s14, v80
	ds_read_b32 v79, v79
	ds_read_b32 v80, v80
	v_add_co_u32_e32 v64, vcc, 0x200, v64
	s_xor_b64 s[14:15], vcc, -1
	s_and_b64 s[14:15], exec, s[14:15]
	v_add_u32_e32 v0, 64, v0
	v_lshl_add_u64 v[66:67], v[66:67], 0, s[44:45]
	v_lshl_add_u64 v[68:69], v[68:69], 0, s[44:45]
	v_lshl_add_u64 v[70:71], v[70:71], 0, s[44:45]
	v_lshl_add_u64 v[72:73], v[72:73], 0, s[44:45]
	s_or_b64 s[0:1], s[14:15], s[0:1]
	s_waitcnt vmcnt(2) lgkmcnt(0)
	v_mul_f32_e32 v81, v76, v80
	v_mul_f32_e32 v80, v75, v80
	v_fma_f32 v75, v75, v79, -v81
	v_fmac_f32_e32 v80, v76, v79
	s_waitcnt vmcnt(0)
	ds_write2st64_b32 v74, v77, v78 offset0:32 offset1:48
	ds_write2st64_b32 v74, v75, v80 offset1:16
	v_add_u32_e32 v74, 0x800, v74
	s_andn2_b64 exec, exec, s[0:1]
	s_cbranch_execnz .LBB0_30
	s_or_b64 exec, exec, s[0:1]
	s_ashr_i32 s64, s62, 5
	s_and_b32 s43, s62, 31
	s_lshl_b32 s0, s64, 9
	s_lshl_b32 s1, s43, 4
	s_or_b32 s46, s1, s0
	s_mov_b64 s[0:1], 0
	v_mov_b32_e32 v0, v88
	v_mov_b32_e32 v64, v173
	s_waitcnt lgkmcnt(0)
	s_barrier
	ds_read_b128 v[100:103], v90 offset:0
	ds_read_b128 v[104:107], v90 offset:16
	ds_read_b128 v[108:111], v90 offset:4096
	ds_read_b128 v[112:115], v90 offset:4112
	v_add_u32_e32 v78, 0, v89
	v_add_u32_e32 v79, 0x1000, v78
	ds_read2_b32 v[116:117], v78 offset0:0 offset1:16
	ds_read2_b32 v[118:119], v78 offset0:32 offset1:48
	ds_read2_b32 v[120:121], v78 offset0:64 offset1:80
	ds_read2_b32 v[122:123], v78 offset0:96 offset1:112
	ds_read2_b32 v[70:71], v79 offset0:0 offset1:16
	ds_read2_b32 v[72:73], v79 offset0:32 offset1:48
	ds_read2_b32 v[74:75], v79 offset0:64 offset1:80
	ds_read2_b32 v[76:77], v79 offset0:96 offset1:112
	s_waitcnt lgkmcnt(0)
	v_mul_f32_e32 v66, v108, v70
	v_mul_f32_e32 v68, v100, v70
	v_fma_f32 v124, v100, v116, -v66
	v_fma_f32 v125, v108, v116, v68
	v_mul_f32_e32 v66, v109, v71
	v_mul_f32_e32 v68, v101, v71
	v_fma_f32 v126, v101, v117, -v66
	v_fma_f32 v127, v109, v117, v68
	v_mul_f32_e32 v66, v110, v72
	v_mul_f32_e32 v68, v102, v72
	v_fma_f32 v128, v102, v118, -v66
	v_fma_f32 v129, v110, v118, v68
	v_mul_f32_e32 v66, v111, v73
	v_mul_f32_e32 v68, v103, v73
	v_fma_f32 v130, v103, v119, -v66
	v_fma_f32 v131, v111, v119, v68
	v_mul_f32_e32 v66, v112, v74
	v_mul_f32_e32 v68, v104, v74
	v_fma_f32 v132, v104, v120, -v66
	v_fma_f32 v133, v112, v120, v68
	v_mul_f32_e32 v66, v113, v75
	v_mul_f32_e32 v68, v105, v75
	v_fma_f32 v134, v105, v121, -v66
	v_fma_f32 v135, v113, v121, v68
	v_mul_f32_e32 v66, v114, v76
	v_mul_f32_e32 v68, v106, v76
	v_fma_f32 v136, v106, v122, -v66
	v_fma_f32 v137, v114, v122, v68
	v_mul_f32_e32 v66, v115, v77
	v_mul_f32_e32 v68, v107, v77
	v_fma_f32 v138, v107, v123, -v66
	v_fma_f32 v139, v115, v123, v68
	ds_read_b128 v[100:103], v90 offset:32
	ds_read_b128 v[104:107], v90 offset:48
	ds_read_b128 v[108:111], v90 offset:4128
	ds_read_b128 v[112:115], v90 offset:4144
	v_add_u32_e32 v78, 0x200, v89
	v_add_u32_e32 v79, 0x1000, v78
	ds_read2_b32 v[116:117], v78 offset0:0 offset1:16
	ds_read2_b32 v[118:119], v78 offset0:32 offset1:48
	ds_read2_b32 v[120:121], v78 offset0:64 offset1:80
	ds_read2_b32 v[122:123], v78 offset0:96 offset1:112
	ds_read2_b32 v[70:71], v79 offset0:0 offset1:16
	ds_read2_b32 v[72:73], v79 offset0:32 offset1:48
	ds_read2_b32 v[74:75], v79 offset0:64 offset1:80
	ds_read2_b32 v[76:77], v79 offset0:96 offset1:112
	s_waitcnt lgkmcnt(0)
	v_mul_f32_e32 v66, v108, v70
	v_mul_f32_e32 v68, v100, v70
	v_fma_f32 v140, v100, v116, -v66
	v_fma_f32 v141, v108, v116, v68
	v_mul_f32_e32 v66, v109, v71
	v_mul_f32_e32 v68, v101, v71
	v_fma_f32 v142, v101, v117, -v66
	v_fma_f32 v143, v109, v117, v68
	v_mul_f32_e32 v66, v110, v72
	v_mul_f32_e32 v68, v102, v72
	v_fma_f32 v144, v102, v118, -v66
	v_fma_f32 v145, v110, v118, v68
	v_mul_f32_e32 v66, v111, v73
	v_mul_f32_e32 v68, v103, v73
	v_fma_f32 v146, v103, v119, -v66
	v_fma_f32 v147, v111, v119, v68
	v_mul_f32_e32 v66, v112, v74
	v_mul_f32_e32 v68, v104, v74
	v_fma_f32 v148, v104, v120, -v66
	v_fma_f32 v149, v112, v120, v68
	v_mul_f32_e32 v66, v113, v75
	v_mul_f32_e32 v68, v105, v75
	v_fma_f32 v150, v105, v121, -v66
	v_fma_f32 v151, v113, v121, v68
	v_mul_f32_e32 v66, v114, v76
	v_mul_f32_e32 v68, v106, v76
	v_fma_f32 v152, v106, v122, -v66
	v_fma_f32 v80, v114, v122, v68
	v_mul_f32_e32 v66, v115, v77
	v_mul_f32_e32 v68, v107, v77
	v_fma_f32 v154, v107, v123, -v66
	v_fma_f32 v155, v115, v123, v68
	ds_read_b128 v[100:103], v90 offset:64
	ds_read_b128 v[104:107], v90 offset:80
	ds_read_b128 v[108:111], v90 offset:4160
	ds_read_b128 v[112:115], v90 offset:4176
	v_add_u32_e32 v78, 0x400, v89
	v_add_u32_e32 v79, 0x1000, v78
	ds_read2_b32 v[116:117], v78 offset0:0 offset1:16
	ds_read2_b32 v[118:119], v78 offset0:32 offset1:48
	ds_read2_b32 v[120:121], v78 offset0:64 offset1:80
	ds_read2_b32 v[122:123], v78 offset0:96 offset1:112
	ds_read2_b32 v[70:71], v79 offset0:0 offset1:16
	ds_read2_b32 v[72:73], v79 offset0:32 offset1:48
	ds_read2_b32 v[74:75], v79 offset0:64 offset1:80
	ds_read2_b32 v[76:77], v79 offset0:96 offset1:112
	s_waitcnt lgkmcnt(0)
	v_mul_f32_e32 v66, v108, v70
	v_mul_f32_e32 v68, v100, v70
	v_fma_f32 v156, v100, v116, -v66
	v_fma_f32 v157, v108, v116, v68
	v_mul_f32_e32 v66, v109, v71
	v_mul_f32_e32 v68, v101, v71
	v_fma_f32 v158, v101, v117, -v66
	v_fma_f32 v159, v109, v117, v68
	v_mul_f32_e32 v66, v110, v72
	v_mul_f32_e32 v68, v102, v72
	v_fma_f32 v160, v102, v118, -v66
	v_fma_f32 v161, v110, v118, v68
	v_mul_f32_e32 v66, v111, v73
	v_mul_f32_e32 v68, v103, v73
	v_fma_f32 v162, v103, v119, -v66
	v_fma_f32 v163, v111, v119, v68
	v_mul_f32_e32 v66, v112, v74
	v_mul_f32_e32 v68, v104, v74
	v_fma_f32 v164, v104, v120, -v66
	v_fma_f32 v165, v112, v120, v68
	v_mul_f32_e32 v66, v113, v75
	v_mul_f32_e32 v68, v105, v75
	v_fma_f32 v166, v105, v121, -v66
	v_fma_f32 v167, v113, v121, v68
	v_mul_f32_e32 v66, v114, v76
	v_mul_f32_e32 v68, v106, v76
	v_fma_f32 v168, v106, v122, -v66
	v_fma_f32 v169, v114, v122, v68
	v_mul_f32_e32 v66, v115, v77
	v_mul_f32_e32 v68, v107, v77
	v_fma_f32 v170, v107, v123, -v66
	v_fma_f32 v171, v115, v123, v68
	ds_read_b128 v[100:103], v90 offset:96
	ds_read_b128 v[104:107], v90 offset:112
	ds_read_b128 v[108:111], v90 offset:4192
	ds_read_b128 v[112:115], v90 offset:4208
	v_add_u32_e32 v78, 0x600, v89
	v_add_u32_e32 v79, 0x1000, v78
	ds_read2_b32 v[116:117], v78 offset0:0 offset1:16
	ds_read2_b32 v[118:119], v78 offset0:32 offset1:48
	ds_read2_b32 v[120:121], v78 offset0:64 offset1:80
	ds_read2_b32 v[122:123], v78 offset0:96 offset1:112
	ds_read2_b32 v[70:71], v79 offset0:0 offset1:16
	ds_read2_b32 v[72:73], v79 offset0:32 offset1:48
	ds_read2_b32 v[74:75], v79 offset0:64 offset1:80
	ds_read2_b32 v[76:77], v79 offset0:96 offset1:112
	s_waitcnt lgkmcnt(0)
	v_mul_f32_e32 v66, v108, v70
	v_mul_f32_e32 v68, v100, v70
	v_fma_f32 v172, v100, v116, -v66
	v_fma_f32 v81, v108, v116, v68
	v_mul_f32_e32 v66, v109, v71
	v_mul_f32_e32 v68, v101, v71
	v_fma_f32 v174, v101, v117, -v66
	v_fma_f32 v175, v109, v117, v68
	v_mul_f32_e32 v66, v110, v72
	v_mul_f32_e32 v68, v102, v72
	v_fma_f32 v176, v102, v118, -v66
	v_fma_f32 v177, v110, v118, v68
	v_mul_f32_e32 v66, v111, v73
	v_mul_f32_e32 v68, v103, v73
	v_fma_f32 v178, v103, v119, -v66
	v_fma_f32 v179, v111, v119, v68
	v_mul_f32_e32 v66, v112, v74
	v_mul_f32_e32 v68, v104, v74
	v_fma_f32 v180, v104, v120, -v66
	v_fma_f32 v181, v112, v120, v68
	v_mul_f32_e32 v66, v113, v75
	v_mul_f32_e32 v68, v105, v75
	v_fma_f32 v182, v105, v121, -v66
	v_fma_f32 v183, v113, v121, v68
	v_mul_f32_e32 v66, v114, v76
	v_mul_f32_e32 v68, v106, v76
	v_fma_f32 v184, v106, v122, -v66
	v_fma_f32 v185, v114, v122, v68
	v_mul_f32_e32 v66, v115, v77
	v_mul_f32_e32 v68, v107, v77
	v_fma_f32 v186, v107, v123, -v66
	v_fma_f32 v187, v115, v123, v68
	ds_read_b128 v[100:103], v90 offset:128
	ds_read_b128 v[104:107], v90 offset:144
	ds_read_b128 v[108:111], v90 offset:4224
	ds_read_b128 v[112:115], v90 offset:4240
	v_add_u32_e32 v78, 0x800, v89
	v_add_u32_e32 v79, 0x1000, v78
	ds_read2_b32 v[116:117], v78 offset0:0 offset1:16
	ds_read2_b32 v[118:119], v78 offset0:32 offset1:48
	ds_read2_b32 v[120:121], v78 offset0:64 offset1:80
	ds_read2_b32 v[122:123], v78 offset0:96 offset1:112
	ds_read2_b32 v[70:71], v79 offset0:0 offset1:16
	ds_read2_b32 v[72:73], v79 offset0:32 offset1:48
	ds_read2_b32 v[74:75], v79 offset0:64 offset1:80
	ds_read2_b32 v[76:77], v79 offset0:96 offset1:112
	s_waitcnt lgkmcnt(0)
	v_mul_f32_e32 v66, v108, v70
	v_mul_f32_e32 v68, v100, v70
	v_fma_f32 v188, v100, v116, -v66
	v_fma_f32 v189, v108, v116, v68
	v_mul_f32_e32 v66, v109, v71
	v_mul_f32_e32 v68, v101, v71
	v_fma_f32 v190, v101, v117, -v66
	v_fma_f32 v191, v109, v117, v68
	v_mul_f32_e32 v66, v110, v72
	v_mul_f32_e32 v68, v102, v72
	v_fma_f32 v192, v102, v118, -v66
	v_fma_f32 v193, v110, v118, v68
	v_mul_f32_e32 v66, v111, v73
	v_mul_f32_e32 v68, v103, v73
	v_fma_f32 v194, v103, v119, -v66
	v_fma_f32 v195, v111, v119, v68
	v_mul_f32_e32 v66, v112, v74
	v_mul_f32_e32 v68, v104, v74
	v_fma_f32 v196, v104, v120, -v66
	v_fma_f32 v197, v112, v120, v68
	v_mul_f32_e32 v66, v113, v75
	v_mul_f32_e32 v68, v105, v75
	v_fma_f32 v198, v105, v121, -v66
	v_fma_f32 v199, v113, v121, v68
	v_mul_f32_e32 v66, v114, v76
	v_mul_f32_e32 v68, v106, v76
	v_fma_f32 v200, v106, v122, -v66
	v_fma_f32 v201, v114, v122, v68
	v_mul_f32_e32 v66, v115, v77
	v_mul_f32_e32 v68, v107, v77
	v_fma_f32 v202, v107, v123, -v66
	v_fma_f32 v203, v115, v123, v68
	ds_read_b128 v[100:103], v90 offset:160
	ds_read_b128 v[104:107], v90 offset:176
	ds_read_b128 v[108:111], v90 offset:4256
	ds_read_b128 v[112:115], v90 offset:4272
	v_add_u32_e32 v78, 0xa00, v89
	v_add_u32_e32 v79, 0x1000, v78
	ds_read2_b32 v[116:117], v78 offset0:0 offset1:16
	ds_read2_b32 v[118:119], v78 offset0:32 offset1:48
	ds_read2_b32 v[120:121], v78 offset0:64 offset1:80
	ds_read2_b32 v[122:123], v78 offset0:96 offset1:112
	ds_read2_b32 v[70:71], v79 offset0:0 offset1:16
	ds_read2_b32 v[72:73], v79 offset0:32 offset1:48
	ds_read2_b32 v[74:75], v79 offset0:64 offset1:80
	ds_read2_b32 v[76:77], v79 offset0:96 offset1:112
	s_waitcnt lgkmcnt(0)
	v_mul_f32_e32 v66, v108, v70
	v_mul_f32_e32 v68, v100, v70
	v_fma_f32 v204, v100, v116, -v66
	v_fma_f32 v205, v108, v116, v68
	v_mul_f32_e32 v66, v109, v71
	v_mul_f32_e32 v68, v101, v71
	v_fma_f32 v206, v101, v117, -v66
	v_fma_f32 v207, v109, v117, v68
	v_mul_f32_e32 v66, v110, v72
	v_mul_f32_e32 v68, v102, v72
	v_fma_f32 v208, v102, v118, -v66
	v_fma_f32 v209, v110, v118, v68
	v_mul_f32_e32 v66, v111, v73
	v_mul_f32_e32 v68, v103, v73
	v_fma_f32 v210, v103, v119, -v66
	v_fma_f32 v211, v111, v119, v68
	v_mul_f32_e32 v66, v112, v74
	v_mul_f32_e32 v68, v104, v74
	v_fma_f32 v212, v104, v120, -v66
	v_fma_f32 v213, v112, v120, v68
	v_mul_f32_e32 v66, v113, v75
	v_mul_f32_e32 v68, v105, v75
	v_fma_f32 v214, v105, v121, -v66
	v_fma_f32 v215, v113, v121, v68
	v_mul_f32_e32 v66, v114, v76
	v_mul_f32_e32 v68, v106, v76
	v_fma_f32 v216, v106, v122, -v66
	v_fma_f32 v217, v114, v122, v68
	v_mul_f32_e32 v66, v115, v77
	v_mul_f32_e32 v68, v107, v77
	v_fma_f32 v218, v107, v123, -v66
	v_fma_f32 v219, v115, v123, v68
	ds_read_b128 v[100:103], v90 offset:192
	ds_read_b128 v[104:107], v90 offset:208
	ds_read_b128 v[108:111], v90 offset:4288
	ds_read_b128 v[112:115], v90 offset:4304
	v_add_u32_e32 v78, 0xc00, v89
	v_add_u32_e32 v79, 0x1000, v78
	ds_read2_b32 v[116:117], v78 offset0:0 offset1:16
	ds_read2_b32 v[118:119], v78 offset0:32 offset1:48
	ds_read2_b32 v[120:121], v78 offset0:64 offset1:80
	ds_read2_b32 v[122:123], v78 offset0:96 offset1:112
	ds_read2_b32 v[70:71], v79 offset0:0 offset1:16
	ds_read2_b32 v[72:73], v79 offset0:32 offset1:48
	ds_read2_b32 v[74:75], v79 offset0:64 offset1:80
	ds_read2_b32 v[76:77], v79 offset0:96 offset1:112
	s_waitcnt lgkmcnt(0)
	v_mul_f32_e32 v66, v108, v70
	v_mul_f32_e32 v68, v100, v70
	v_fma_f32 v220, v100, v116, -v66
	v_fma_f32 v221, v108, v116, v68
	v_mul_f32_e32 v66, v109, v71
	v_mul_f32_e32 v68, v101, v71
	v_fma_f32 v222, v101, v117, -v66
	v_fma_f32 v223, v109, v117, v68
	v_mul_f32_e32 v66, v110, v72
	v_mul_f32_e32 v68, v102, v72
	v_fma_f32 v224, v102, v118, -v66
	v_fma_f32 v225, v110, v118, v68
	v_mul_f32_e32 v66, v111, v73
	v_mul_f32_e32 v68, v103, v73
	v_fma_f32 v226, v103, v119, -v66
	v_fma_f32 v227, v111, v119, v68
	v_mul_f32_e32 v66, v112, v74
	v_mul_f32_e32 v68, v104, v74
	v_fma_f32 v228, v104, v120, -v66
	v_fma_f32 v229, v112, v120, v68
	v_mul_f32_e32 v66, v113, v75
	v_mul_f32_e32 v68, v105, v75
	v_fma_f32 v230, v105, v121, -v66
	v_fma_f32 v231, v113, v121, v68
	v_mul_f32_e32 v66, v114, v76
	v_mul_f32_e32 v68, v106, v76
	v_fma_f32 v232, v106, v122, -v66
	v_fma_f32 v233, v114, v122, v68
	v_mul_f32_e32 v66, v115, v77
	v_mul_f32_e32 v68, v107, v77
	v_fma_f32 v234, v107, v123, -v66
	v_fma_f32 v235, v115, v123, v68
	ds_read_b128 v[100:103], v90 offset:224
	ds_read_b128 v[104:107], v90 offset:240
	ds_read_b128 v[108:111], v90 offset:4320
	ds_read_b128 v[112:115], v90 offset:4336
	v_add_u32_e32 v78, 0xe00, v89
	v_add_u32_e32 v79, 0x1000, v78
	ds_read2_b32 v[116:117], v78 offset0:0 offset1:16
	ds_read2_b32 v[118:119], v78 offset0:32 offset1:48
	ds_read2_b32 v[120:121], v78 offset0:64 offset1:80
	ds_read2_b32 v[122:123], v78 offset0:96 offset1:112
	ds_read2_b32 v[70:71], v79 offset0:0 offset1:16
	ds_read2_b32 v[72:73], v79 offset0:32 offset1:48
	ds_read2_b32 v[74:75], v79 offset0:64 offset1:80
	ds_read2_b32 v[76:77], v79 offset0:96 offset1:112
	s_waitcnt lgkmcnt(0)
	v_mul_f32_e32 v66, v108, v70
	v_mul_f32_e32 v68, v100, v70
	v_fma_f32 v236, v100, v116, -v66
	v_fma_f32 v237, v108, v116, v68
	v_mul_f32_e32 v66, v109, v71
	v_mul_f32_e32 v68, v101, v71
	v_fma_f32 v238, v101, v117, -v66
	v_fma_f32 v239, v109, v117, v68
	v_mul_f32_e32 v66, v110, v72
	v_mul_f32_e32 v68, v102, v72
	v_fma_f32 v240, v102, v118, -v66
	v_fma_f32 v241, v110, v118, v68
	v_mul_f32_e32 v66, v111, v73
	v_mul_f32_e32 v68, v103, v73
	v_fma_f32 v242, v103, v119, -v66
	v_fma_f32 v243, v111, v119, v68
	v_mul_f32_e32 v66, v112, v74
	v_mul_f32_e32 v68, v104, v74
	v_fma_f32 v244, v104, v120, -v66
	v_fma_f32 v245, v112, v120, v68
	v_mul_f32_e32 v66, v113, v75
	v_mul_f32_e32 v68, v105, v75
	v_fma_f32 v246, v105, v121, -v66
	v_fma_f32 v247, v113, v121, v68
	v_mul_f32_e32 v66, v114, v76
	v_mul_f32_e32 v68, v106, v76
	v_fma_f32 v248, v106, v122, -v66
	v_fma_f32 v249, v114, v122, v68
	v_mul_f32_e32 v66, v115, v77
	v_mul_f32_e32 v68, v107, v77
	v_fma_f32 v250, v107, v123, -v66
	v_fma_f32 v251, v115, v123, v68
	s_nop 0
	s_nop 0
	s_nop 0
	s_nop 0
	s_nop 0
	s_nop 0
	s_nop 0
	s_nop 0
	s_nop 0
	s_nop 0
	s_nop 0
	s_nop 0
	s_nop 0
	s_nop 0
	s_nop 0
	s_nop 0
	s_nop 0
	s_nop 0
	s_nop 0
	s_nop 0
	s_nop 0
	s_nop 0
	s_nop 0
	s_nop 0
	s_nop 0
	s_nop 0
	s_nop 0
	s_nop 0
	s_nop 0
	s_nop 0
	s_nop 0
	s_nop 0
	s_nop 0
	s_nop 0
	s_nop 0
	s_nop 0
	s_nop 0
	s_nop 0
	s_nop 0
	s_nop 0
	s_nop 0
	s_nop 0
	s_nop 0
	s_nop 0
	s_nop 0
	s_nop 0
	s_nop 0
	s_nop 0
	s_nop 0
	s_nop 0
	s_nop 0
	s_nop 0
	s_nop 0
	s_nop 0
	s_nop 0
	s_nop 0
	s_nop 0
	s_nop 0
	s_nop 0
	s_nop 0
	s_nop 0
	s_nop 0
	s_nop 0
	s_branch .LBB0_33

.LBB0_162:
	v_ashrrev_i32_e32 v7, 31, v6
	s_waitcnt lgkmcnt(0)
	v_lshlrev_b64 v[16:17], 12, v[6:7]
	v_lshl_add_u64 v[28:29], v[4:5], 0, v[16:17]
	v_lshlrev_b64 v[20:21], 11, v[6:7]
	v_lshl_add_u64 v[32:33], v[0:1], 0, v[20:21]
	global_load_dwordx4 v[16:19], v[28:29], off
	global_load_dwordx4 v[20:23], v[28:29], off offset:1024
	global_load_dwordx4 v[24:27], v[28:29], off offset:2048
	global_load_dwordx4 v[28:31], v[28:29], off offset:3072
	s_waitcnt vmcnt(3)
	v_cvt_pk_bf16_f32 v48, v16, v17
	v_cvt_pk_bf16_f32 v49, v18, v19
	global_store_dwordx2 v[32:33], v[48:49], off
	s_waitcnt vmcnt(3)
	v_cvt_pk_bf16_f32 v50, v20, v21
	v_cvt_pk_bf16_f32 v51, v22, v23
	global_store_dwordx2 v[32:33], v[50:51], off offset:512
	s_waitcnt vmcnt(3)
	v_cvt_pk_bf16_f32 v52, v24, v25
	v_cvt_pk_bf16_f32 v53, v26, v27
	global_store_dwordx2 v[32:33], v[52:53], off offset:1024
	v_cmp_lt_i32_e64 s[0:1], v10, v9
	v_mul_f32_e32 v17, v17, v17
	v_mul_f32_e32 v19, v19, v19
	v_fmac_f32_e32 v17, v16, v16
	v_fmac_f32_e32 v19, v18, v18
	v_add_f32_e32 v16, v17, v19
	v_mul_f32_e32 v17, v21, v21
	v_mul_f32_e32 v18, v23, v23
	v_fmac_f32_e32 v17, v20, v20
	v_fmac_f32_e32 v18, v22, v22
	v_add_f32_e32 v17, v17, v18
	v_add_f32_e32 v16, v16, v17
	v_mul_f32_e32 v17, v25, v25
	v_mul_f32_e32 v18, v27, v27
	v_fmac_f32_e32 v17, v24, v24
	v_fmac_f32_e32 v18, v26, v26
	v_add_f32_e32 v17, v17, v18
	v_add_f32_e32 v16, v16, v17
	s_waitcnt vmcnt(3)
	v_mul_f32_e32 v17, v29, v29
	v_mul_f32_e32 v18, v31, v31
	v_fmac_f32_e32 v17, v28, v28
	v_fmac_f32_e32 v18, v30, v30
	v_cndmask_b32_e64 v34, v8, v10, s[0:1]
	v_add_f32_e32 v17, v17, v18
	v_lshlrev_b32_e32 v34, 2, v34
	v_add_f32_e32 v16, v16, v17
	ds_bpermute_b32 v17, v34, v16
	v_cmp_lt_i32_e64 s[0:1], v11, v9
	s_waitcnt lgkmcnt(0)
	v_add_f32_e32 v16, v16, v17
	v_cndmask_b32_e64 v18, v8, v11, s[0:1]
	v_lshlrev_b32_e32 v18, 2, v18
	ds_bpermute_b32 v17, v18, v16
	s_waitcnt lgkmcnt(0)
	v_add_f32_e32 v16, v16, v17
	s_nop 1
	v_add_f32_dpp v16, v16, v16 row_ror:8 row_mask:0xf bank_mask:0xf
	s_nop 1
	v_add_f32_dpp v16, v16, v16 row_ror:4 row_mask:0xf bank_mask:0xf
	s_nop 1
	v_add_f32_dpp v16, v16, v16 row_ror:2 row_mask:0xf bank_mask:0xf
	s_nop 1
	v_add_f32_dpp v16, v16, v16 row_ror:1 row_mask:0xf bank_mask:0xf
	v_mov_b32_e32 v17, 0
	v_cvt_pk_bf16_f32 v18, v28, v29
	v_cvt_pk_bf16_f32 v19, v30, v31
	global_store_dwordx2 v[32:33], v[18:19], off offset:1536
	s_and_saveexec_b64 s[0:1], vcc
	s_cbranch_execz .LBB0_161
	s_waitcnt lgkmcnt(0)
	v_add_f32_e32 v16, v16, v17
	v_cndmask_b32_e64 v18, 0, v16, s[2:3]
	v_lshlrev_b64 v[16:17], 6, v[6:7]
	v_lshl_add_u64 v[16:17], v[2:3], 0, v[16:17]
	global_store_dword v[16:17], v18, off
	s_branch .LBB0_161
